# K=4096 GEMM loops: DMA staging rebalanced 4+4 per load segment (saddr form), s_setprio removed
# speedup vs baseline: 1.1570x; 1.1570x over previous
; #define PG8_STAGE(bufoff, gbase, voff) do { _Pragma("unroll") for (int _i = 0; _i < 2; ++_i) \
;         __builtin_amdgcn_global_load_lds((const unsigned*)((const char*)(gbase) + (voff)[_i]), (PG8_LAS unsigned*)(lds + (bufoff) + ldsw + _i * 8192), 16, 0, 0); } while (0)
; #define PG8_STAGE_NT(bufoff, gbase, voff) do { _Pragma("unroll") for (int _i = 0; _i < 2; ++_i) \
;         __builtin_amdgcn_global_load_lds((const unsigned*)((const char*)(gbase) + (voff)[_i]), (PG8_LAS unsigned*)(lds + (bufoff) + ldsw + _i * 8192), 16, 0, PG8_B_AUX); } while (0)
; #define PG8_LDA(dst, b, h) do { _Pragma("unroll") for (int m = 0; m < 4; ++m) _Pragma("unroll") for (int k = 0; k < 2; ++k) dst[m][k] = *(const PG8_LAS bf16x8*)(lds + PG8_SA(b, h) + aoff + m * 2048 + k * 1024); } while (0)
; #define PG8_LDB(dst, b, h) do { _Pragma("unroll") for (int n = 0; n < 2; ++n) _Pragma("unroll") for (int k = 0; k < 2; ++k) dst[n][k] = *(const PG8_LAS bf16x8*)(lds + PG8_SB(b, h) + boff + n * 2048 + k * 1024); } while (0)
; #define PG8_WAIT_V(n) asm volatile("s_waitcnt vmcnt(" #n ")" ::: "memory")
; #define PG8_WAIT_L(n) asm volatile("s_waitcnt lgkmcnt(" #n ")" ::: "memory")
; #define PG8_BAR __builtin_amdgcn_s_barrier()
; template <class Epi, class Sched, bool ALIGN_EPI = false, bool SP2 = false>
; __device__ __forceinline__ void gemm_phase(PG8_LAS unsigned char* lds, const Gemm g, const Sched& S, const Epi& E, int wid) {
;     ...
;         for (int t = 0; t < nt; t += 2) {
;             const bool last = (t == nt - 2);
;             const char* a1 = cA + (size_t)(t + 1) * kstep;
;             const char* a2 = last ? nA : cA + (size_t)(t + 2) * kstep; const char* b2 = last ? nB : cB + (size_t)(t + 2) * kstep;
;             const char* a3 = a2 + kstep; const char* b3 = b2 + kstep;
;             if (last && has_next) S.a_ready(nxt);
;             if constexpr (SP2) {
;             PG8_LDB(B0, 0, 0); PG8_LDB(B1, 0, 1); PG8_SCHED; PG8_LDA(At, 0, 0); PG8_STAGE(PG8_SA(1, 1), a1 + hstepA, voffA);
;             PG8_WAIT_V(8); PG8_WAIT_L(0); PG8_BAR; PG8_MMA(0, 0, At, B0); PG8_MMA(0, 1, At, B1); PG8_BAR; PG8_SCHED;
;             PG8_LDA(At, 0, 1); PG8_STAGE_NT(PG8_SB(0, 0), b2, voffB); PG8_STAGE_NT(PG8_SB(0, 1), b2 + hstepB, voffB); PG8_STAGE(PG8_SA(0, 0), a2, voffA);
;             PG8_WAIT_V(8); PG8_WAIT_L(0); PG8_BAR; PG8_MMA(1, 0, At, B0); PG8_MMA(1, 1, At, B1); PG8_BAR; PG8_SCHED;
.LBB0_233:
	ds_read_b128 v[144:147], v155
	ds_read_b128 v[148:151], v155 offset:1024
	ds_read_b128 v[160:163], v155 offset:2048
	ds_read_b128 v[164:167], v155 offset:3072
	ds_read_b128 v[168:171], v156
	ds_read_b128 v[172:175], v156 offset:1024
	ds_read_b128 v[176:179], v156 offset:2048
	ds_read_b128 v[180:183], v156 offset:3072
	s_add_u32 s4, s48, 0x100
	s_addc_u32 s5, s49, 0
	s_add_u32 s98, s48, 0x80
	s_addc_u32 s99, s49, 0
	s_add_u32 s100, s48, 0x104080
	s_addc_u32 s101, s49, 0
	s_cmp_eq_u32 s66, 60
	s_cselect_b32 s53, s45, s5
	s_cselect_b32 s52, s44, s4
	s_cselect_b32 s51, s47, s65
	s_cselect_b32 s50, s46, s64
	s_add_i32 m0, s23, 0xc000
	ds_read_b128 v[184:187], v157
	ds_read_b128 v[188:191], v157 offset:1024
	ds_read_b128 v[192:195], v157 offset:2048
	ds_read_b128 v[196:199], v157 offset:3072
	ds_read_b128 v[200:203], v157 offset:4096
	ds_read_b128 v[204:207], v157 offset:5120
	ds_read_b128 v[208:211], v157 offset:6144
	ds_read_b128 v[212:215], v157 offset:7168
	global_load_lds_dwordx4 v134, s[100:101]
	s_add_i32 m0, s23, 0xe000
	s_nop 0
	global_load_lds_dwordx4 v130, s[100:101]
	s_mov_b32 m0, s55
	s_nop 0
	global_load_lds_dwordx4 v134, s[98:99]
	s_mov_b32 m0, s56
	s_nop 0
	global_load_lds_dwordx4 v130, s[98:99]
	s_waitcnt vmcnt(8)
	s_waitcnt lgkmcnt(0)
	s_barrier
	s_waitcnt lgkmcnt(0)
	v_mfma_f32_16x16x32_bf16 v[112:115], v[144:147], v[184:187], v[112:115]
	v_mfma_f32_16x16x32_bf16 v[108:111], v[160:163], v[184:187], v[108:111]
	v_mfma_f32_16x16x32_bf16 v[104:107], v[144:147], v[192:195], v[104:107]
	v_mfma_f32_16x16x32_bf16 v[100:103], v[160:163], v[192:195], v[100:103]
	v_mfma_f32_16x16x32_bf16 v[92:95], v[144:147], v[200:203], v[92:95]
	v_mfma_f32_16x16x32_bf16 v[84:87], v[160:163], v[200:203], v[84:87]
	v_mfma_f32_16x16x32_bf16 v[76:79], v[144:147], v[208:211], v[76:79]
	v_mfma_f32_16x16x32_bf16 v[68:71], v[160:163], v[208:211], v[68:71]
	v_mfma_f32_16x16x32_bf16 v[112:115], v[148:151], v[188:191], v[112:115]
	v_mfma_f32_16x16x32_bf16 v[108:111], v[164:167], v[188:191], v[108:111]
	v_mfma_f32_16x16x32_bf16 v[104:107], v[148:151], v[196:199], v[104:107]
	v_mfma_f32_16x16x32_bf16 v[100:103], v[164:167], v[196:199], v[100:103]
	v_mfma_f32_16x16x32_bf16 v[92:95], v[148:151], v[204:207], v[92:95]
	v_mfma_f32_16x16x32_bf16 v[84:87], v[164:167], v[204:207], v[84:87]
	v_mfma_f32_16x16x32_bf16 v[76:79], v[148:151], v[212:215], v[76:79]
	v_mfma_f32_16x16x32_bf16 v[68:71], v[164:167], v[212:215], v[68:71]
	v_mfma_f32_16x16x32_bf16 v[124:127], v[168:171], v[184:187], v[124:127]
	v_mfma_f32_16x16x32_bf16 v[120:123], v[176:179], v[184:187], v[120:123]
	v_mfma_f32_16x16x32_bf16 v[116:119], v[168:171], v[192:195], v[116:119]
	v_mfma_f32_16x16x32_bf16 v[96:99], v[176:179], v[192:195], v[96:99]
	v_mfma_f32_16x16x32_bf16 v[88:91], v[168:171], v[200:203], v[88:91]
	v_mfma_f32_16x16x32_bf16 v[80:83], v[176:179], v[200:203], v[80:83]
	v_mfma_f32_16x16x32_bf16 v[72:75], v[168:171], v[208:211], v[72:75]
	v_mfma_f32_16x16x32_bf16 v[64:67], v[176:179], v[208:211], v[64:67]
	v_mfma_f32_16x16x32_bf16 v[124:127], v[172:175], v[188:191], v[124:127]
	v_mfma_f32_16x16x32_bf16 v[120:123], v[180:183], v[188:191], v[120:123]
	v_mfma_f32_16x16x32_bf16 v[116:119], v[172:175], v[196:199], v[116:119]
	v_mfma_f32_16x16x32_bf16 v[96:99], v[180:183], v[196:199], v[96:99]
	v_mfma_f32_16x16x32_bf16 v[88:91], v[172:175], v[204:207], v[88:91]
	v_mfma_f32_16x16x32_bf16 v[80:83], v[180:183], v[204:207], v[80:83]
	v_mfma_f32_16x16x32_bf16 v[72:75], v[172:175], v[212:215], v[72:75]
	v_mfma_f32_16x16x32_bf16 v[64:67], v[180:183], v[212:215], v[64:67]
	s_barrier
	s_add_i32 s48, s58, s17
	s_mov_b32 m0, s48
	ds_read_b128 v[184:187], v157 offset:16384
	ds_read_b128 v[188:191], v157 offset:17408
	ds_read_b128 v[192:195], v157 offset:18432
	ds_read_b128 v[196:199], v157 offset:19456
	ds_read_b128 v[200:203], v157 offset:20480
	ds_read_b128 v[204:207], v157 offset:21504
	ds_read_b128 v[208:211], v157 offset:22528
	ds_read_b128 v[212:215], v157 offset:23552
	global_load_lds_dwordx4 v132, s[50:51]
	s_add_i32 m0, s48, 0x2000
	s_add_u32 s48, s50, 0x104000
	s_addc_u32 s49, s51, 0
	s_add_i32 s67, s59, s17
	global_load_lds_dwordx4 v128, s[50:51]
	s_mov_b32 m0, s67
	s_nop 0
	global_load_lds_dwordx4 v132, s[48:49]
	s_add_i32 m0, s67, 0x2000
	s_nop 0
	global_load_lds_dwordx4 v128, s[48:49]
	s_waitcnt vmcnt(4)
	s_waitcnt lgkmcnt(0)
	s_barrier
	s_waitcnt lgkmcnt(0)
	v_mfma_f32_16x16x32_bf16 v[60:63], v[144:147], v[184:187], v[60:63]
	v_mfma_f32_16x16x32_bf16 v[52:55], v[160:163], v[184:187], v[52:55]
	v_mfma_f32_16x16x32_bf16 v[44:47], v[144:147], v[192:195], v[44:47]
	v_mfma_f32_16x16x32_bf16 v[36:39], v[160:163], v[192:195], v[36:39]
	v_mfma_f32_16x16x32_bf16 v[28:31], v[144:147], v[200:203], v[28:31]
	v_mfma_f32_16x16x32_bf16 v[20:23], v[160:163], v[200:203], v[20:23]
	v_mfma_f32_16x16x32_bf16 v[12:15], v[144:147], v[208:211], v[12:15]
	v_mfma_f32_16x16x32_bf16 v[4:7], v[160:163], v[208:211], v[4:7]
	v_mfma_f32_16x16x32_bf16 v[60:63], v[148:151], v[188:191], v[60:63]
	v_mfma_f32_16x16x32_bf16 v[52:55], v[164:167], v[188:191], v[52:55]
	v_mfma_f32_16x16x32_bf16 v[44:47], v[148:151], v[196:199], v[44:47]
	v_mfma_f32_16x16x32_bf16 v[36:39], v[164:167], v[196:199], v[36:39]
	v_mfma_f32_16x16x32_bf16 v[28:31], v[148:151], v[204:207], v[28:31]
	v_mfma_f32_16x16x32_bf16 v[20:23], v[164:167], v[204:207], v[20:23]
	v_mfma_f32_16x16x32_bf16 v[12:15], v[148:151], v[212:215], v[12:15]
	v_mfma_f32_16x16x32_bf16 v[4:7], v[164:167], v[212:215], v[4:7]
	v_mfma_f32_16x16x32_bf16 v[56:59], v[168:171], v[184:187], v[56:59]
	v_mfma_f32_16x16x32_bf16 v[48:51], v[176:179], v[184:187], v[48:51]
	v_mfma_f32_16x16x32_bf16 v[40:43], v[168:171], v[192:195], v[40:43]
	v_mfma_f32_16x16x32_bf16 v[32:35], v[176:179], v[192:195], v[32:35]
	v_mfma_f32_16x16x32_bf16 v[24:27], v[168:171], v[200:203], v[24:27]
	v_mfma_f32_16x16x32_bf16 v[16:19], v[176:179], v[200:203], v[16:19]
	v_mfma_f32_16x16x32_bf16 v[8:11], v[168:171], v[208:211], v[8:11]
	v_mfma_f32_16x16x32_bf16 v[0:3], v[176:179], v[208:211], v[0:3]
	v_mfma_f32_16x16x32_bf16 v[56:59], v[172:175], v[188:191], v[56:59]
	v_mfma_f32_16x16x32_bf16 v[48:51], v[180:183], v[188:191], v[48:51]
	v_mfma_f32_16x16x32_bf16 v[40:43], v[172:175], v[196:199], v[40:43]
	v_mfma_f32_16x16x32_bf16 v[32:35], v[180:183], v[196:199], v[32:35]
	v_mfma_f32_16x16x32_bf16 v[24:27], v[172:175], v[204:207], v[24:27]
	v_mfma_f32_16x16x32_bf16 v[16:19], v[180:183], v[204:207], v[16:19]
	v_mfma_f32_16x16x32_bf16 v[8:11], v[172:175], v[212:215], v[8:11]
	v_mfma_f32_16x16x32_bf16 v[0:3], v[180:183], v[212:215], v[0:3]
	s_barrier
; #define PG8_STAGE(bufoff, gbase, voff) do { _Pragma("unroll") for (int _i = 0; _i < 2; ++_i) \
;         __builtin_amdgcn_global_load_lds((const unsigned*)((const char*)(gbase) + (voff)[_i]), (PG8_LAS unsigned*)(lds + (bufoff) + ldsw + _i * 8192), 16, 0, 0); } while (0)
; template <class Epi, class Sched, bool ALIGN_EPI = false, bool SP2 = false>
; __device__ __forceinline__ void gemm_phase(PG8_LAS unsigned char* lds, const Gemm g, const Sched& S, const Epi& E, int wid) {
;     ...
;             PG8_LDB(B0, 1, 0); PG8_LDB(B1, 1, 1); PG8_SCHED; PG8_LDA(At, 1, 0); PG8_STAGE(PG8_SA(0, 1), a2 + hstepA, voffA);
;             PG8_WAIT_V(8); PG8_WAIT_L(0); PG8_BAR; PG8_MMA(0, 0, At, B0); PG8_MMA(0, 1, At, B1); PG8_BAR; PG8_SCHED;
;             PG8_LDA(At, 1, 1); PG8_STAGE_NT(PG8_SB(1, 0), b3, voffB); PG8_STAGE_NT(PG8_SB(1, 1), b3 + hstepB, voffB); PG8_STAGE(PG8_SA(1, 0), a3, voffA);
;             PG8_WAIT_V(8); PG8_WAIT_L(0); PG8_BAR; PG8_MMA(1, 0, At, B0); PG8_MMA(1, 1, At, B1); PG8_BAR; PG8_SCHED;
;             } else {
;             PG8_LDB(B0, 0, 0); PG8_SCHED; PG8_LDA(At, 0, 0); PG8_STAGE(PG8_SA(1, 1), a1 + hstepA, voffA);
;             PG8_WAIT_L(8); PG8_BAR; PG8_WAIT_L(0); PG8_MMA(0, 0, At, B0); PG8_BAR; PG8_SCHED;
;             PG8_LDB(B1, 0, 1); PG8_STAGE_NT(PG8_SB(0, 0), b2, voffB);
;             PG8_BAR; PG8_WAIT_L(0); PG8_MMA(0, 1, At, B1); PG8_BAR;
;             PG8_LDA(At, 0, 1); PG8_STAGE(PG8_SA(0, 0), a2, voffA);
;             PG8_BAR; PG8_WAIT_L(0); PG8_MMA(1, 0, At, B0); PG8_BAR; PG8_SCHED;
;             PG8_STAGE_NT(PG8_SB(0, 1), b2 + hstepB, voffB);
;             PG8_WAIT_V(6); PG8_BAR; PG8_MMA(1, 1, At, B1); PG8_BAR;
;             PG8_LDB(B0, 1, 0); PG8_SCHED; PG8_LDA(At, 1, 0); PG8_STAGE(PG8_SA(0, 1), a2 + hstepA, voffA);
;             PG8_WAIT_L(8); PG8_BAR; PG8_WAIT_L(0); PG8_MMA(0, 0, At, B0); PG8_BAR; PG8_SCHED;
;             PG8_LDB(B1, 1, 1); PG8_STAGE_NT(PG8_SB(1, 0), b3, voffB);
;             PG8_BAR; PG8_WAIT_L(0); PG8_MMA(0, 1, At, B1); PG8_BAR;
;             PG8_LDA(At, 1, 1); PG8_STAGE(PG8_SA(1, 0), a3, voffA);
;             PG8_BAR; PG8_WAIT_L(0); PG8_MMA(1, 0, At, B0); PG8_BAR; PG8_SCHED;
;             PG8_STAGE_NT(PG8_SB(1, 1), b3 + hstepB, voffB);
;             PG8_WAIT_V(6); PG8_BAR; PG8_MMA(1, 1, At, B1); PG8_BAR;
;             }
;         }
;         if constexpr (ALIGN_EPI) { if (wr == 0) PG8_BAR; }
	s_add_i32 s67, 0, 0x18000
	v_add_u32_e32 v159, s67, v153
	s_add_i32 s68, 0, 0x1c000
	ds_read_b128 v[144:147], v159
	ds_read_b128 v[148:151], v159 offset:1024
	ds_read_b128 v[160:163], v159 offset:2048
	ds_read_b128 v[164:167], v159 offset:3072
	v_add_u32_e32 v159, s68, v153
	ds_read_b128 v[168:171], v159
	ds_read_b128 v[172:175], v159 offset:1024
	ds_read_b128 v[176:179], v159 offset:2048
	ds_read_b128 v[180:183], v159 offset:3072
	s_add_u32 s48, s52, 0x104000
	s_addc_u32 s49, s53, 0
	s_mov_b32 m0, s25
	ds_read_b128 v[184:187], v157 offset:32768
	ds_read_b128 v[188:191], v157 offset:33792
	ds_read_b128 v[192:195], v157 offset:34816
	ds_read_b128 v[196:199], v157 offset:35840
	ds_read_b128 v[200:203], v157 offset:36864
	ds_read_b128 v[204:207], v157 offset:37888
	ds_read_b128 v[208:211], v157 offset:38912
	ds_read_b128 v[212:215], v157 offset:39936
	global_load_lds_dwordx4 v134, s[48:49]
	s_mov_b32 m0, s29
	s_nop 0
	global_load_lds_dwordx4 v130, s[48:49]
	s_mov_b32 m0, s23
	s_nop 0
	global_load_lds_dwordx4 v134, s[52:53]
	s_mov_b32 m0, s24
	s_nop 0
	global_load_lds_dwordx4 v130, s[52:53]
	s_waitcnt vmcnt(8)
	s_waitcnt lgkmcnt(0)
	s_barrier
	s_waitcnt lgkmcnt(0)
	v_mfma_f32_16x16x32_bf16 v[112:115], v[144:147], v[184:187], v[112:115]
	v_mfma_f32_16x16x32_bf16 v[108:111], v[160:163], v[184:187], v[108:111]
	v_mfma_f32_16x16x32_bf16 v[104:107], v[144:147], v[192:195], v[104:107]
	v_mfma_f32_16x16x32_bf16 v[100:103], v[160:163], v[192:195], v[100:103]
	v_mfma_f32_16x16x32_bf16 v[92:95], v[144:147], v[200:203], v[92:95]
	v_mfma_f32_16x16x32_bf16 v[84:87], v[160:163], v[200:203], v[84:87]
	v_mfma_f32_16x16x32_bf16 v[76:79], v[144:147], v[208:211], v[76:79]
	v_mfma_f32_16x16x32_bf16 v[68:71], v[160:163], v[208:211], v[68:71]
	v_mfma_f32_16x16x32_bf16 v[112:115], v[148:151], v[188:191], v[112:115]
	v_mfma_f32_16x16x32_bf16 v[108:111], v[164:167], v[188:191], v[108:111]
	v_mfma_f32_16x16x32_bf16 v[104:107], v[148:151], v[196:199], v[104:107]
	v_mfma_f32_16x16x32_bf16 v[100:103], v[164:167], v[196:199], v[100:103]
	v_mfma_f32_16x16x32_bf16 v[92:95], v[148:151], v[204:207], v[92:95]
	v_mfma_f32_16x16x32_bf16 v[84:87], v[164:167], v[204:207], v[84:87]
	v_mfma_f32_16x16x32_bf16 v[76:79], v[148:151], v[212:215], v[76:79]
	v_mfma_f32_16x16x32_bf16 v[68:71], v[164:167], v[212:215], v[68:71]
	v_mfma_f32_16x16x32_bf16 v[124:127], v[168:171], v[184:187], v[124:127]
	v_mfma_f32_16x16x32_bf16 v[120:123], v[176:179], v[184:187], v[120:123]
	v_mfma_f32_16x16x32_bf16 v[116:119], v[168:171], v[192:195], v[116:119]
	v_mfma_f32_16x16x32_bf16 v[96:99], v[176:179], v[192:195], v[96:99]
	v_mfma_f32_16x16x32_bf16 v[88:91], v[168:171], v[200:203], v[88:91]
	v_mfma_f32_16x16x32_bf16 v[80:83], v[176:179], v[200:203], v[80:83]
	v_mfma_f32_16x16x32_bf16 v[72:75], v[168:171], v[208:211], v[72:75]
	v_mfma_f32_16x16x32_bf16 v[64:67], v[176:179], v[208:211], v[64:67]
	v_mfma_f32_16x16x32_bf16 v[124:127], v[172:175], v[188:191], v[124:127]
	v_mfma_f32_16x16x32_bf16 v[120:123], v[180:183], v[188:191], v[120:123]
	v_mfma_f32_16x16x32_bf16 v[116:119], v[172:175], v[196:199], v[116:119]
	v_mfma_f32_16x16x32_bf16 v[96:99], v[180:183], v[196:199], v[96:99]
	v_mfma_f32_16x16x32_bf16 v[88:91], v[172:175], v[204:207], v[88:91]
	v_mfma_f32_16x16x32_bf16 v[80:83], v[180:183], v[204:207], v[80:83]
	v_mfma_f32_16x16x32_bf16 v[72:75], v[172:175], v[212:215], v[72:75]
	v_mfma_f32_16x16x32_bf16 v[64:67], v[180:183], v[212:215], v[64:67]
	s_barrier
	s_add_i32 s48, s67, s17
	s_mov_b32 m0, s48
	s_add_u32 s98, s50, 0x80
	s_addc_u32 s99, s51, 0
	ds_read_b128 v[184:187], v157 offset:49152
	ds_read_b128 v[188:191], v157 offset:50176
	ds_read_b128 v[192:195], v157 offset:51200
	ds_read_b128 v[196:199], v157 offset:52224
	ds_read_b128 v[200:203], v157 offset:53248
	ds_read_b128 v[204:207], v157 offset:54272
	ds_read_b128 v[208:211], v157 offset:55296
	ds_read_b128 v[212:215], v157 offset:56320
	global_load_lds_dwordx4 v132, s[98:99]
	s_add_i32 m0, s48, 0x2000
	s_add_u32 s48, s50, 0x104080
	s_addc_u32 s49, s51, 0
	s_add_i32 s50, s68, s17
	global_load_lds_dwordx4 v128, s[98:99]
	s_mov_b32 m0, s50
	s_nop 0
	global_load_lds_dwordx4 v132, s[48:49]
	s_add_i32 m0, s50, 0x2000
	s_nop 0
	global_load_lds_dwordx4 v128, s[48:49]
	s_waitcnt vmcnt(4)
	s_waitcnt lgkmcnt(0)
	s_barrier
	s_waitcnt lgkmcnt(0)
	v_mfma_f32_16x16x32_bf16 v[60:63], v[144:147], v[184:187], v[60:63]
	v_mfma_f32_16x16x32_bf16 v[52:55], v[160:163], v[184:187], v[52:55]
	v_mfma_f32_16x16x32_bf16 v[44:47], v[144:147], v[192:195], v[44:47]
	v_mfma_f32_16x16x32_bf16 v[36:39], v[160:163], v[192:195], v[36:39]
	v_mfma_f32_16x16x32_bf16 v[28:31], v[144:147], v[200:203], v[28:31]
	v_mfma_f32_16x16x32_bf16 v[20:23], v[160:163], v[200:203], v[20:23]
	v_mfma_f32_16x16x32_bf16 v[12:15], v[144:147], v[208:211], v[12:15]
	v_mfma_f32_16x16x32_bf16 v[4:7], v[160:163], v[208:211], v[4:7]
	v_mfma_f32_16x16x32_bf16 v[60:63], v[148:151], v[188:191], v[60:63]
	v_mfma_f32_16x16x32_bf16 v[52:55], v[164:167], v[188:191], v[52:55]
	v_mfma_f32_16x16x32_bf16 v[44:47], v[148:151], v[196:199], v[44:47]
	v_mfma_f32_16x16x32_bf16 v[36:39], v[164:167], v[196:199], v[36:39]
	v_mfma_f32_16x16x32_bf16 v[28:31], v[148:151], v[204:207], v[28:31]
	v_mfma_f32_16x16x32_bf16 v[20:23], v[164:167], v[204:207], v[20:23]
	v_mfma_f32_16x16x32_bf16 v[12:15], v[148:151], v[212:215], v[12:15]
	v_mfma_f32_16x16x32_bf16 v[4:7], v[164:167], v[212:215], v[4:7]
	v_mfma_f32_16x16x32_bf16 v[56:59], v[168:171], v[184:187], v[56:59]
	v_mfma_f32_16x16x32_bf16 v[48:51], v[176:179], v[184:187], v[48:51]
	v_mfma_f32_16x16x32_bf16 v[40:43], v[168:171], v[192:195], v[40:43]
	v_mfma_f32_16x16x32_bf16 v[32:35], v[176:179], v[192:195], v[32:35]
	v_mfma_f32_16x16x32_bf16 v[24:27], v[168:171], v[200:203], v[24:27]
	v_mfma_f32_16x16x32_bf16 v[16:19], v[176:179], v[200:203], v[16:19]
	v_mfma_f32_16x16x32_bf16 v[8:11], v[168:171], v[208:211], v[8:11]
	v_mfma_f32_16x16x32_bf16 v[0:3], v[176:179], v[208:211], v[0:3]
	v_mfma_f32_16x16x32_bf16 v[56:59], v[172:175], v[188:191], v[56:59]
	v_mfma_f32_16x16x32_bf16 v[48:51], v[180:183], v[188:191], v[48:51]
	v_mfma_f32_16x16x32_bf16 v[40:43], v[172:175], v[196:199], v[40:43]
	v_mfma_f32_16x16x32_bf16 v[32:35], v[180:183], v[196:199], v[32:35]
	v_mfma_f32_16x16x32_bf16 v[24:27], v[172:175], v[204:207], v[24:27]
	v_mfma_f32_16x16x32_bf16 v[16:19], v[180:183], v[204:207], v[16:19]
	v_mfma_f32_16x16x32_bf16 v[8:11], v[172:175], v[212:215], v[8:11]
	v_mfma_f32_16x16x32_bf16 v[0:3], v[180:183], v[212:215], v[0:3]
	s_barrier
	s_add_i32 s66, s66, 2
	s_add_u32 s64, s64, 0x100
	s_addc_u32 s65, s65, 0
	s_cmp_gt_u32 s66, 61
	s_mov_b64 s[48:49], s[4:5]
	s_cbranch_scc0 .LBB0_233
	s_and_b64 vcc, exec, s[42:43]
	s_cbranch_vccz .LBB0_236
	s_barrier

; #define PG8_STAGE(bufoff, gbase, voff) do { _Pragma("unroll") for (int _i = 0; _i < 2; ++_i) \
;         __builtin_amdgcn_global_load_lds((const unsigned*)((const char*)(gbase) + (voff)[_i]), (PG8_LAS unsigned*)(lds + (bufoff) + ldsw + _i * 8192), 16, 0, 0); } while (0)
; #define PG8_STAGE_NT(bufoff, gbase, voff) do { _Pragma("unroll") for (int _i = 0; _i < 2; ++_i) \
;         __builtin_amdgcn_global_load_lds((const unsigned*)((const char*)(gbase) + (voff)[_i]), (PG8_LAS unsigned*)(lds + (bufoff) + ldsw + _i * 8192), 16, 0, PG8_B_AUX); } while (0)
; #define PG8_LDA(dst, b, h) do { _Pragma("unroll") for (int m = 0; m < 4; ++m) _Pragma("unroll") for (int k = 0; k < 2; ++k) dst[m][k] = *(const PG8_LAS bf16x8*)(lds + PG8_SA(b, h) + aoff + m * 2048 + k * 1024); } while (0)
; #define PG8_LDB(dst, b, h) do { _Pragma("unroll") for (int n = 0; n < 2; ++n) _Pragma("unroll") for (int k = 0; k < 2; ++k) dst[n][k] = *(const PG8_LAS bf16x8*)(lds + PG8_SB(b, h) + boff + n * 2048 + k * 1024); } while (0)
; #define PG8_WAIT_V(n) asm volatile("s_waitcnt vmcnt(" #n ")" ::: "memory")
; #define PG8_WAIT_L(n) asm volatile("s_waitcnt lgkmcnt(" #n ")" ::: "memory")
; #define PG8_BAR __builtin_amdgcn_s_barrier()
; template <class Epi, class Sched, bool ALIGN_EPI = false, bool SP2 = false>
; __device__ __forceinline__ void gemm_phase(PG8_LAS unsigned char* lds, const Gemm g, const Sched& S, const Epi& E, int wid) {
;     ...
;         for (int t = 0; t < nt; t += 2) {
;             const bool last = (t == nt - 2);
;             const char* a1 = cA + (size_t)(t + 1) * kstep;
;             const char* a2 = last ? nA : cA + (size_t)(t + 2) * kstep; const char* b2 = last ? nB : cB + (size_t)(t + 2) * kstep;
;             const char* a3 = a2 + kstep; const char* b3 = b2 + kstep;
;             if (last && has_next) S.a_ready(nxt);
;             if constexpr (SP2) {
;             PG8_LDB(B0, 0, 0); PG8_LDB(B1, 0, 1); PG8_SCHED; PG8_LDA(At, 0, 0); PG8_STAGE(PG8_SA(1, 1), a1 + hstepA, voffA);
;             PG8_WAIT_V(8); PG8_WAIT_L(0); PG8_BAR; PG8_MMA(0, 0, At, B0); PG8_MMA(0, 1, At, B1); PG8_BAR; PG8_SCHED;
;             PG8_LDA(At, 0, 1); PG8_STAGE_NT(PG8_SB(0, 0), b2, voffB); PG8_STAGE_NT(PG8_SB(0, 1), b2 + hstepB, voffB); PG8_STAGE(PG8_SA(0, 0), a2, voffA);
;             PG8_WAIT_V(8); PG8_WAIT_L(0); PG8_BAR; PG8_MMA(1, 0, At, B0); PG8_MMA(1, 1, At, B1); PG8_BAR; PG8_SCHED;
.LBB0_426:
	ds_read_b128 v[144:147], v161
	ds_read_b128 v[148:151], v161 offset:1024
	ds_read_b128 v[152:155], v161 offset:2048
	ds_read_b128 v[166:169], v161 offset:3072
	ds_read_b128 v[170:173], v162
	ds_read_b128 v[174:177], v162 offset:1024
	ds_read_b128 v[178:181], v162 offset:2048
	ds_read_b128 v[182:185], v162 offset:3072
	s_add_u32 s4, s46, 0x100
	s_addc_u32 s5, s47, 0
	s_add_u32 s98, s46, 0x80
	s_addc_u32 s99, s47, 0
	s_add_u32 s100, s46, 0x104080
	s_addc_u32 s101, s47, 0
	s_cmp_eq_u32 s64, 60
	s_cselect_b32 s51, s43, s5
	s_cselect_b32 s50, s42, s4
	s_cselect_b32 s49, s45, s63
	s_cselect_b32 s48, s44, s62
	s_add_i32 m0, s23, 0xc000
	ds_read_b128 v[186:189], v163
	ds_read_b128 v[190:193], v163 offset:1024
	ds_read_b128 v[194:197], v163 offset:2048
	ds_read_b128 v[198:201], v163 offset:3072
	ds_read_b128 v[202:205], v163 offset:4096
	ds_read_b128 v[206:209], v163 offset:5120
	ds_read_b128 v[210:213], v163 offset:6144
	ds_read_b128 v[214:217], v163 offset:7168
	global_load_lds_dwordx4 v134, s[100:101]
	s_add_i32 m0, s23, 0xe000
	s_nop 0
	global_load_lds_dwordx4 v130, s[100:101]
	s_mov_b32 m0, s53
	s_nop 0
	global_load_lds_dwordx4 v134, s[98:99]
	s_mov_b32 m0, s54
	s_nop 0
	global_load_lds_dwordx4 v130, s[98:99]
	s_waitcnt vmcnt(8)
	s_waitcnt lgkmcnt(0)
	s_barrier
	s_waitcnt lgkmcnt(0)
	v_mfma_f32_16x16x32_bf16 v[124:127], v[144:147], v[186:189], v[124:127]
	v_mfma_f32_16x16x32_bf16 v[120:123], v[152:155], v[186:189], v[120:123]
	v_mfma_f32_16x16x32_bf16 v[116:119], v[144:147], v[194:197], v[116:119]
	v_mfma_f32_16x16x32_bf16 v[112:115], v[152:155], v[194:197], v[112:115]
	v_mfma_f32_16x16x32_bf16 v[92:95], v[144:147], v[202:205], v[92:95]
	v_mfma_f32_16x16x32_bf16 v[88:91], v[152:155], v[202:205], v[88:91]
	v_mfma_f32_16x16x32_bf16 v[76:79], v[144:147], v[210:213], v[76:79]
	v_mfma_f32_16x16x32_bf16 v[72:75], v[152:155], v[210:213], v[72:75]
	v_mfma_f32_16x16x32_bf16 v[124:127], v[148:151], v[190:193], v[124:127]
	v_mfma_f32_16x16x32_bf16 v[120:123], v[166:169], v[190:193], v[120:123]
	v_mfma_f32_16x16x32_bf16 v[116:119], v[148:151], v[198:201], v[116:119]
	v_mfma_f32_16x16x32_bf16 v[112:115], v[166:169], v[198:201], v[112:115]
	v_mfma_f32_16x16x32_bf16 v[92:95], v[148:151], v[206:209], v[92:95]
	v_mfma_f32_16x16x32_bf16 v[88:91], v[166:169], v[206:209], v[88:91]
	v_mfma_f32_16x16x32_bf16 v[76:79], v[148:151], v[214:217], v[76:79]
	v_mfma_f32_16x16x32_bf16 v[72:75], v[166:169], v[214:217], v[72:75]
	v_mfma_f32_16x16x32_bf16 v[108:111], v[170:173], v[186:189], v[108:111]
	v_mfma_f32_16x16x32_bf16 v[104:107], v[178:181], v[186:189], v[104:107]
	v_mfma_f32_16x16x32_bf16 v[100:103], v[170:173], v[194:197], v[100:103]
	v_mfma_f32_16x16x32_bf16 v[96:99], v[178:181], v[194:197], v[96:99]
	v_mfma_f32_16x16x32_bf16 v[84:87], v[170:173], v[202:205], v[84:87]
	v_mfma_f32_16x16x32_bf16 v[80:83], v[178:181], v[202:205], v[80:83]
	v_mfma_f32_16x16x32_bf16 v[68:71], v[170:173], v[210:213], v[68:71]
	v_mfma_f32_16x16x32_bf16 v[64:67], v[178:181], v[210:213], v[64:67]
	v_mfma_f32_16x16x32_bf16 v[108:111], v[174:177], v[190:193], v[108:111]
	v_mfma_f32_16x16x32_bf16 v[104:107], v[182:185], v[190:193], v[104:107]
	v_mfma_f32_16x16x32_bf16 v[100:103], v[174:177], v[198:201], v[100:103]
	v_mfma_f32_16x16x32_bf16 v[96:99], v[182:185], v[198:201], v[96:99]
	v_mfma_f32_16x16x32_bf16 v[84:87], v[174:177], v[206:209], v[84:87]
	v_mfma_f32_16x16x32_bf16 v[80:83], v[182:185], v[206:209], v[80:83]
	v_mfma_f32_16x16x32_bf16 v[68:71], v[174:177], v[214:217], v[68:71]
	v_mfma_f32_16x16x32_bf16 v[64:67], v[182:185], v[214:217], v[64:67]
	s_barrier
	s_add_i32 s46, s56, s17
	s_mov_b32 m0, s46
	ds_read_b128 v[186:189], v163 offset:16384
	ds_read_b128 v[190:193], v163 offset:17408
	ds_read_b128 v[194:197], v163 offset:18432
	ds_read_b128 v[198:201], v163 offset:19456
	ds_read_b128 v[202:205], v163 offset:20480
	ds_read_b128 v[206:209], v163 offset:21504
	ds_read_b128 v[210:213], v163 offset:22528
	ds_read_b128 v[214:217], v163 offset:23552
	global_load_lds_dwordx4 v132, s[48:49]
	s_add_i32 m0, s46, 0x2000
	s_add_u32 s46, s48, 0x104000
	s_addc_u32 s47, s49, 0
	s_add_i32 s65, s57, s17
	global_load_lds_dwordx4 v128, s[48:49]
	s_mov_b32 m0, s65
	s_nop 0
	global_load_lds_dwordx4 v132, s[46:47]
	s_add_i32 m0, s65, 0x2000
	s_nop 0
	global_load_lds_dwordx4 v128, s[46:47]
	s_waitcnt vmcnt(4)
	s_waitcnt lgkmcnt(0)
	s_barrier
	s_waitcnt lgkmcnt(0)
	v_mfma_f32_16x16x32_bf16 v[60:63], v[144:147], v[186:189], v[60:63]
	v_mfma_f32_16x16x32_bf16 v[56:59], v[152:155], v[186:189], v[56:59]
	v_mfma_f32_16x16x32_bf16 v[44:47], v[144:147], v[194:197], v[44:47]
	v_mfma_f32_16x16x32_bf16 v[40:43], v[152:155], v[194:197], v[40:43]
	v_mfma_f32_16x16x32_bf16 v[28:31], v[144:147], v[202:205], v[28:31]
	v_mfma_f32_16x16x32_bf16 v[24:27], v[152:155], v[202:205], v[24:27]
	v_mfma_f32_16x16x32_bf16 v[12:15], v[144:147], v[210:213], v[12:15]
	v_mfma_f32_16x16x32_bf16 v[8:11], v[152:155], v[210:213], v[8:11]
	v_mfma_f32_16x16x32_bf16 v[60:63], v[148:151], v[190:193], v[60:63]
	v_mfma_f32_16x16x32_bf16 v[56:59], v[166:169], v[190:193], v[56:59]
	v_mfma_f32_16x16x32_bf16 v[44:47], v[148:151], v[198:201], v[44:47]
	v_mfma_f32_16x16x32_bf16 v[40:43], v[166:169], v[198:201], v[40:43]
	v_mfma_f32_16x16x32_bf16 v[28:31], v[148:151], v[206:209], v[28:31]
	v_mfma_f32_16x16x32_bf16 v[24:27], v[166:169], v[206:209], v[24:27]
	v_mfma_f32_16x16x32_bf16 v[12:15], v[148:151], v[214:217], v[12:15]
	v_mfma_f32_16x16x32_bf16 v[8:11], v[166:169], v[214:217], v[8:11]
	v_mfma_f32_16x16x32_bf16 v[52:55], v[170:173], v[186:189], v[52:55]
	v_mfma_f32_16x16x32_bf16 v[48:51], v[178:181], v[186:189], v[48:51]
	v_mfma_f32_16x16x32_bf16 v[36:39], v[170:173], v[194:197], v[36:39]
	v_mfma_f32_16x16x32_bf16 v[32:35], v[178:181], v[194:197], v[32:35]
	v_mfma_f32_16x16x32_bf16 v[20:23], v[170:173], v[202:205], v[20:23]
	v_mfma_f32_16x16x32_bf16 v[16:19], v[178:181], v[202:205], v[16:19]
	v_mfma_f32_16x16x32_bf16 v[4:7], v[170:173], v[210:213], v[4:7]
	v_mfma_f32_16x16x32_bf16 v[0:3], v[178:181], v[210:213], v[0:3]
	v_mfma_f32_16x16x32_bf16 v[52:55], v[174:177], v[190:193], v[52:55]
	v_mfma_f32_16x16x32_bf16 v[48:51], v[182:185], v[190:193], v[48:51]
	v_mfma_f32_16x16x32_bf16 v[36:39], v[174:177], v[198:201], v[36:39]
	v_mfma_f32_16x16x32_bf16 v[32:35], v[182:185], v[198:201], v[32:35]
	v_mfma_f32_16x16x32_bf16 v[20:23], v[174:177], v[206:209], v[20:23]
	v_mfma_f32_16x16x32_bf16 v[16:19], v[182:185], v[206:209], v[16:19]
	v_mfma_f32_16x16x32_bf16 v[4:7], v[174:177], v[214:217], v[4:7]
	v_mfma_f32_16x16x32_bf16 v[0:3], v[182:185], v[214:217], v[0:3]
	s_barrier
; #define PG8_STAGE(bufoff, gbase, voff) do { _Pragma("unroll") for (int _i = 0; _i < 2; ++_i) \
;         __builtin_amdgcn_global_load_lds((const unsigned*)((const char*)(gbase) + (voff)[_i]), (PG8_LAS unsigned*)(lds + (bufoff) + ldsw + _i * 8192), 16, 0, 0); } while (0)
; template <class Epi, class Sched, bool ALIGN_EPI = false, bool SP2 = false>
; __device__ __forceinline__ void gemm_phase(PG8_LAS unsigned char* lds, const Gemm g, const Sched& S, const Epi& E, int wid) {
;     ...
;             PG8_LDB(B0, 1, 0); PG8_LDB(B1, 1, 1); PG8_SCHED; PG8_LDA(At, 1, 0); PG8_STAGE(PG8_SA(0, 1), a2 + hstepA, voffA);
;             PG8_WAIT_V(8); PG8_WAIT_L(0); PG8_BAR; PG8_MMA(0, 0, At, B0); PG8_MMA(0, 1, At, B1); PG8_BAR; PG8_SCHED;
;             PG8_LDA(At, 1, 1); PG8_STAGE_NT(PG8_SB(1, 0), b3, voffB); PG8_STAGE_NT(PG8_SB(1, 1), b3 + hstepB, voffB); PG8_STAGE(PG8_SA(1, 0), a3, voffA);
;             PG8_WAIT_V(8); PG8_WAIT_L(0); PG8_BAR; PG8_MMA(1, 0, At, B0); PG8_MMA(1, 1, At, B1); PG8_BAR; PG8_SCHED;
;             } else {
;             PG8_LDB(B0, 0, 0); PG8_SCHED; PG8_LDA(At, 0, 0); PG8_STAGE(PG8_SA(1, 1), a1 + hstepA, voffA);
;             PG8_WAIT_L(8); PG8_BAR; PG8_WAIT_L(0); PG8_MMA(0, 0, At, B0); PG8_BAR; PG8_SCHED;
;             PG8_LDB(B1, 0, 1); PG8_STAGE_NT(PG8_SB(0, 0), b2, voffB);
;             PG8_BAR; PG8_WAIT_L(0); PG8_MMA(0, 1, At, B1); PG8_BAR;
;             PG8_LDA(At, 0, 1); PG8_STAGE(PG8_SA(0, 0), a2, voffA);
;             PG8_BAR; PG8_WAIT_L(0); PG8_MMA(1, 0, At, B0); PG8_BAR; PG8_SCHED;
;             PG8_STAGE_NT(PG8_SB(0, 1), b2 + hstepB, voffB);
;             PG8_WAIT_V(6); PG8_BAR; PG8_MMA(1, 1, At, B1); PG8_BAR;
;             PG8_LDB(B0, 1, 0); PG8_SCHED; PG8_LDA(At, 1, 0); PG8_STAGE(PG8_SA(0, 1), a2 + hstepA, voffA);
;             PG8_WAIT_L(8); PG8_BAR; PG8_WAIT_L(0); PG8_MMA(0, 0, At, B0); PG8_BAR; PG8_SCHED;
;             PG8_LDB(B1, 1, 1); PG8_STAGE_NT(PG8_SB(1, 0), b3, voffB);
;             PG8_BAR; PG8_WAIT_L(0); PG8_MMA(0, 1, At, B1); PG8_BAR;
;             PG8_LDA(At, 1, 1); PG8_STAGE(PG8_SA(1, 0), a3, voffA);
;             PG8_BAR; PG8_WAIT_L(0); PG8_MMA(1, 0, At, B0); PG8_BAR; PG8_SCHED;
;             PG8_STAGE_NT(PG8_SB(1, 1), b3 + hstepB, voffB);
;             PG8_WAIT_V(6); PG8_BAR; PG8_MMA(1, 1, At, B1); PG8_BAR;
;             }
;         }
;         if constexpr (ALIGN_EPI) { if (wr == 0) PG8_BAR; }
	s_add_i32 s65, 0, 0x18000
	v_add_u32_e32 v165, s65, v159
	s_add_i32 s66, 0, 0x1c000
	ds_read_b128 v[144:147], v165
	ds_read_b128 v[148:151], v165 offset:1024
	ds_read_b128 v[152:155], v165 offset:2048
	ds_read_b128 v[166:169], v165 offset:3072
	v_add_u32_e32 v165, s66, v159
	ds_read_b128 v[170:173], v165
	ds_read_b128 v[174:177], v165 offset:1024
	ds_read_b128 v[178:181], v165 offset:2048
	ds_read_b128 v[182:185], v165 offset:3072
	s_add_u32 s46, s50, 0x104000
	s_addc_u32 s47, s51, 0
	s_mov_b32 m0, s25
	ds_read_b128 v[186:189], v163 offset:32768
	ds_read_b128 v[190:193], v163 offset:33792
	ds_read_b128 v[194:197], v163 offset:34816
	ds_read_b128 v[198:201], v163 offset:35840
	ds_read_b128 v[202:205], v163 offset:36864
	ds_read_b128 v[206:209], v163 offset:37888
	ds_read_b128 v[210:213], v163 offset:38912
	ds_read_b128 v[214:217], v163 offset:39936
	global_load_lds_dwordx4 v134, s[46:47]
	s_mov_b32 m0, s29
	s_nop 0
	global_load_lds_dwordx4 v130, s[46:47]
	s_mov_b32 m0, s23
	s_nop 0
	global_load_lds_dwordx4 v134, s[50:51]
	s_mov_b32 m0, s24
	s_nop 0
	global_load_lds_dwordx4 v130, s[50:51]
	s_waitcnt vmcnt(8)
	s_waitcnt lgkmcnt(0)
	s_barrier
	s_waitcnt lgkmcnt(0)
	v_mfma_f32_16x16x32_bf16 v[124:127], v[144:147], v[186:189], v[124:127]
	v_mfma_f32_16x16x32_bf16 v[120:123], v[152:155], v[186:189], v[120:123]
	v_mfma_f32_16x16x32_bf16 v[116:119], v[144:147], v[194:197], v[116:119]
	v_mfma_f32_16x16x32_bf16 v[112:115], v[152:155], v[194:197], v[112:115]
	v_mfma_f32_16x16x32_bf16 v[92:95], v[144:147], v[202:205], v[92:95]
	v_mfma_f32_16x16x32_bf16 v[88:91], v[152:155], v[202:205], v[88:91]
	v_mfma_f32_16x16x32_bf16 v[76:79], v[144:147], v[210:213], v[76:79]
	v_mfma_f32_16x16x32_bf16 v[72:75], v[152:155], v[210:213], v[72:75]
	v_mfma_f32_16x16x32_bf16 v[124:127], v[148:151], v[190:193], v[124:127]
	v_mfma_f32_16x16x32_bf16 v[120:123], v[166:169], v[190:193], v[120:123]
	v_mfma_f32_16x16x32_bf16 v[116:119], v[148:151], v[198:201], v[116:119]
	v_mfma_f32_16x16x32_bf16 v[112:115], v[166:169], v[198:201], v[112:115]
	v_mfma_f32_16x16x32_bf16 v[92:95], v[148:151], v[206:209], v[92:95]
	v_mfma_f32_16x16x32_bf16 v[88:91], v[166:169], v[206:209], v[88:91]
	v_mfma_f32_16x16x32_bf16 v[76:79], v[148:151], v[214:217], v[76:79]
	v_mfma_f32_16x16x32_bf16 v[72:75], v[166:169], v[214:217], v[72:75]
	v_mfma_f32_16x16x32_bf16 v[108:111], v[170:173], v[186:189], v[108:111]
	v_mfma_f32_16x16x32_bf16 v[104:107], v[178:181], v[186:189], v[104:107]
	v_mfma_f32_16x16x32_bf16 v[100:103], v[170:173], v[194:197], v[100:103]
	v_mfma_f32_16x16x32_bf16 v[96:99], v[178:181], v[194:197], v[96:99]
	v_mfma_f32_16x16x32_bf16 v[84:87], v[170:173], v[202:205], v[84:87]
	v_mfma_f32_16x16x32_bf16 v[80:83], v[178:181], v[202:205], v[80:83]
	v_mfma_f32_16x16x32_bf16 v[68:71], v[170:173], v[210:213], v[68:71]
	v_mfma_f32_16x16x32_bf16 v[64:67], v[178:181], v[210:213], v[64:67]
	v_mfma_f32_16x16x32_bf16 v[108:111], v[174:177], v[190:193], v[108:111]
	v_mfma_f32_16x16x32_bf16 v[104:107], v[182:185], v[190:193], v[104:107]
	v_mfma_f32_16x16x32_bf16 v[100:103], v[174:177], v[198:201], v[100:103]
	v_mfma_f32_16x16x32_bf16 v[96:99], v[182:185], v[198:201], v[96:99]
	v_mfma_f32_16x16x32_bf16 v[84:87], v[174:177], v[206:209], v[84:87]
	v_mfma_f32_16x16x32_bf16 v[80:83], v[182:185], v[206:209], v[80:83]
	v_mfma_f32_16x16x32_bf16 v[68:71], v[174:177], v[214:217], v[68:71]
	v_mfma_f32_16x16x32_bf16 v[64:67], v[182:185], v[214:217], v[64:67]
	s_barrier
	s_add_i32 s46, s65, s17
	s_mov_b32 m0, s46
	s_add_u32 s98, s48, 0x80
	s_addc_u32 s99, s49, 0
	ds_read_b128 v[186:189], v163 offset:49152
	ds_read_b128 v[190:193], v163 offset:50176
	ds_read_b128 v[194:197], v163 offset:51200
	ds_read_b128 v[198:201], v163 offset:52224
	ds_read_b128 v[202:205], v163 offset:53248
	ds_read_b128 v[206:209], v163 offset:54272
	ds_read_b128 v[210:213], v163 offset:55296
	ds_read_b128 v[214:217], v163 offset:56320
	global_load_lds_dwordx4 v132, s[98:99]
	s_add_i32 m0, s46, 0x2000
	s_add_u32 s46, s48, 0x104080
	s_addc_u32 s47, s49, 0
	s_add_i32 s48, s66, s17
	global_load_lds_dwordx4 v128, s[98:99]
	s_mov_b32 m0, s48
	s_nop 0
	global_load_lds_dwordx4 v132, s[46:47]
	s_add_i32 m0, s48, 0x2000
	s_nop 0
	global_load_lds_dwordx4 v128, s[46:47]
	s_waitcnt vmcnt(4)
	s_waitcnt lgkmcnt(0)
	s_barrier
	s_waitcnt lgkmcnt(0)
	v_mfma_f32_16x16x32_bf16 v[60:63], v[144:147], v[186:189], v[60:63]
	v_mfma_f32_16x16x32_bf16 v[56:59], v[152:155], v[186:189], v[56:59]
	v_mfma_f32_16x16x32_bf16 v[44:47], v[144:147], v[194:197], v[44:47]
	v_mfma_f32_16x16x32_bf16 v[40:43], v[152:155], v[194:197], v[40:43]
	v_mfma_f32_16x16x32_bf16 v[28:31], v[144:147], v[202:205], v[28:31]
	v_mfma_f32_16x16x32_bf16 v[24:27], v[152:155], v[202:205], v[24:27]
	v_mfma_f32_16x16x32_bf16 v[12:15], v[144:147], v[210:213], v[12:15]
	v_mfma_f32_16x16x32_bf16 v[8:11], v[152:155], v[210:213], v[8:11]
	v_mfma_f32_16x16x32_bf16 v[60:63], v[148:151], v[190:193], v[60:63]
	v_mfma_f32_16x16x32_bf16 v[56:59], v[166:169], v[190:193], v[56:59]
	v_mfma_f32_16x16x32_bf16 v[44:47], v[148:151], v[198:201], v[44:47]
	v_mfma_f32_16x16x32_bf16 v[40:43], v[166:169], v[198:201], v[40:43]
	v_mfma_f32_16x16x32_bf16 v[28:31], v[148:151], v[206:209], v[28:31]
	v_mfma_f32_16x16x32_bf16 v[24:27], v[166:169], v[206:209], v[24:27]
	v_mfma_f32_16x16x32_bf16 v[12:15], v[148:151], v[214:217], v[12:15]
	v_mfma_f32_16x16x32_bf16 v[8:11], v[166:169], v[214:217], v[8:11]
	v_mfma_f32_16x16x32_bf16 v[52:55], v[170:173], v[186:189], v[52:55]
	v_mfma_f32_16x16x32_bf16 v[48:51], v[178:181], v[186:189], v[48:51]
	v_mfma_f32_16x16x32_bf16 v[36:39], v[170:173], v[194:197], v[36:39]
	v_mfma_f32_16x16x32_bf16 v[32:35], v[178:181], v[194:197], v[32:35]
	v_mfma_f32_16x16x32_bf16 v[20:23], v[170:173], v[202:205], v[20:23]
	v_mfma_f32_16x16x32_bf16 v[16:19], v[178:181], v[202:205], v[16:19]
	v_mfma_f32_16x16x32_bf16 v[4:7], v[170:173], v[210:213], v[4:7]
	v_mfma_f32_16x16x32_bf16 v[0:3], v[178:181], v[210:213], v[0:3]
	v_mfma_f32_16x16x32_bf16 v[52:55], v[174:177], v[190:193], v[52:55]
	v_mfma_f32_16x16x32_bf16 v[48:51], v[182:185], v[190:193], v[48:51]
	v_mfma_f32_16x16x32_bf16 v[36:39], v[174:177], v[198:201], v[36:39]
	v_mfma_f32_16x16x32_bf16 v[32:35], v[182:185], v[198:201], v[32:35]
	v_mfma_f32_16x16x32_bf16 v[20:23], v[174:177], v[206:209], v[20:23]
	v_mfma_f32_16x16x32_bf16 v[16:19], v[182:185], v[206:209], v[16:19]
	v_mfma_f32_16x16x32_bf16 v[4:7], v[174:177], v[214:217], v[4:7]
	v_mfma_f32_16x16x32_bf16 v[0:3], v[182:185], v[214:217], v[0:3]
	s_barrier
	s_add_i32 s64, s64, 2
	s_add_u32 s62, s62, 0x100
	s_addc_u32 s63, s63, 0
	s_cmp_gt_u32 s64, 61
	s_mov_b64 s[46:47], s[4:5]
	s_cbranch_scc0 .LBB0_426
	s_and_b64 vcc, exec, s[40:41]
	s_cbranch_vccz .LBB0_429
	s_barrier

; #define PG8_STAGE(bufoff, gbase, voff) do { _Pragma("unroll") for (int _i = 0; _i < 2; ++_i) \
;         __builtin_amdgcn_global_load_lds((const unsigned*)((const char*)(gbase) + (voff)[_i]), (PG8_LAS unsigned*)(lds + (bufoff) + ldsw + _i * 8192), 16, 0, 0); } while (0)
; #define PG8_STAGE_NT(bufoff, gbase, voff) do { _Pragma("unroll") for (int _i = 0; _i < 2; ++_i) \
;         __builtin_amdgcn_global_load_lds((const unsigned*)((const char*)(gbase) + (voff)[_i]), (PG8_LAS unsigned*)(lds + (bufoff) + ldsw + _i * 8192), 16, 0, PG8_B_AUX); } while (0)
; #define PG8_LDA(dst, b, h) do { _Pragma("unroll") for (int m = 0; m < 4; ++m) _Pragma("unroll") for (int k = 0; k < 2; ++k) dst[m][k] = *(const PG8_LAS bf16x8*)(lds + PG8_SA(b, h) + aoff + m * 2048 + k * 1024); } while (0)
; #define PG8_LDB(dst, b, h) do { _Pragma("unroll") for (int n = 0; n < 2; ++n) _Pragma("unroll") for (int k = 0; k < 2; ++k) dst[n][k] = *(const PG8_LAS bf16x8*)(lds + PG8_SB(b, h) + boff + n * 2048 + k * 1024); } while (0)
; #define PG8_WAIT_V(n) asm volatile("s_waitcnt vmcnt(" #n ")" ::: "memory")
; #define PG8_WAIT_L(n) asm volatile("s_waitcnt lgkmcnt(" #n ")" ::: "memory")
; #define PG8_BAR __builtin_amdgcn_s_barrier()
; template <class Epi, class Sched, bool ALIGN_EPI = false, bool SP2 = false>
; __device__ __forceinline__ void gemm_phase(PG8_LAS unsigned char* lds, const Gemm g, const Sched& S, const Epi& E, int wid) {
;     ...
;         for (int t = 0; t < nt; t += 2) {
;             const bool last = (t == nt - 2);
;             const char* a1 = cA + (size_t)(t + 1) * kstep;
;             const char* a2 = last ? nA : cA + (size_t)(t + 2) * kstep; const char* b2 = last ? nB : cB + (size_t)(t + 2) * kstep;
;             const char* a3 = a2 + kstep; const char* b3 = b2 + kstep;
;             if (last && has_next) S.a_ready(nxt);
;             if constexpr (SP2) {
;             PG8_LDB(B0, 0, 0); PG8_LDB(B1, 0, 1); PG8_SCHED; PG8_LDA(At, 0, 0); PG8_STAGE(PG8_SA(1, 1), a1 + hstepA, voffA);
;             PG8_WAIT_V(8); PG8_WAIT_L(0); PG8_BAR; PG8_MMA(0, 0, At, B0); PG8_MMA(0, 1, At, B1); PG8_BAR; PG8_SCHED;
;             PG8_LDA(At, 0, 1); PG8_STAGE_NT(PG8_SB(0, 0), b2, voffB); PG8_STAGE_NT(PG8_SB(0, 1), b2 + hstepB, voffB); PG8_STAGE(PG8_SA(0, 0), a2, voffA);
;             PG8_WAIT_V(8); PG8_WAIT_L(0); PG8_BAR; PG8_MMA(1, 0, At, B0); PG8_MMA(1, 1, At, B1); PG8_BAR; PG8_SCHED;
.LBB0_1133:
	ds_read_b128 v[144:147], v155
	ds_read_b128 v[148:151], v155 offset:1024
	ds_read_b128 v[160:163], v155 offset:2048
	ds_read_b128 v[164:167], v155 offset:3072
	ds_read_b128 v[168:171], v156
	ds_read_b128 v[172:175], v156 offset:1024
	ds_read_b128 v[176:179], v156 offset:2048
	ds_read_b128 v[180:183], v156 offset:3072
	s_add_u32 s4, s46, 0x100
	s_addc_u32 s5, s47, 0
	s_add_u32 s98, s46, 0x80
	s_addc_u32 s99, s47, 0
	s_add_u32 s100, s46, 0x104080
	s_addc_u32 s101, s47, 0
	s_cmp_eq_u32 s63, 60
	s_cselect_b32 s51, s43, s5
	s_cselect_b32 s50, s42, s4
	s_cselect_b32 s49, s45, s62
	s_cselect_b32 s48, s44, s61
	s_add_i32 m0, s22, 0xc000
	ds_read_b128 v[184:187], v157
	ds_read_b128 v[188:191], v157 offset:1024
	ds_read_b128 v[192:195], v157 offset:2048
	ds_read_b128 v[196:199], v157 offset:3072
	ds_read_b128 v[200:203], v157 offset:4096
	ds_read_b128 v[204:207], v157 offset:5120
	ds_read_b128 v[208:211], v157 offset:6144
	ds_read_b128 v[212:215], v157 offset:7168
	global_load_lds_dwordx4 v134, s[100:101]
	s_add_i32 m0, s22, 0xe000
	s_nop 0
	global_load_lds_dwordx4 v130, s[100:101]
	s_mov_b32 m0, s52
	s_nop 0
	global_load_lds_dwordx4 v134, s[98:99]
	s_mov_b32 m0, s53
	s_nop 0
	global_load_lds_dwordx4 v130, s[98:99]
	s_waitcnt vmcnt(8)
	s_waitcnt lgkmcnt(0)
	s_barrier
	s_waitcnt lgkmcnt(0)
	v_mfma_f32_16x16x32_bf16 v[112:115], v[144:147], v[184:187], v[112:115]
	v_mfma_f32_16x16x32_bf16 v[108:111], v[160:163], v[184:187], v[108:111]
	v_mfma_f32_16x16x32_bf16 v[104:107], v[144:147], v[192:195], v[104:107]
	v_mfma_f32_16x16x32_bf16 v[100:103], v[160:163], v[192:195], v[100:103]
	v_mfma_f32_16x16x32_bf16 v[92:95], v[144:147], v[200:203], v[92:95]
	v_mfma_f32_16x16x32_bf16 v[84:87], v[160:163], v[200:203], v[84:87]
	v_mfma_f32_16x16x32_bf16 v[76:79], v[144:147], v[208:211], v[76:79]
	v_mfma_f32_16x16x32_bf16 v[68:71], v[160:163], v[208:211], v[68:71]
	v_mfma_f32_16x16x32_bf16 v[112:115], v[148:151], v[188:191], v[112:115]
	v_mfma_f32_16x16x32_bf16 v[108:111], v[164:167], v[188:191], v[108:111]
	v_mfma_f32_16x16x32_bf16 v[104:107], v[148:151], v[196:199], v[104:107]
	v_mfma_f32_16x16x32_bf16 v[100:103], v[164:167], v[196:199], v[100:103]
	v_mfma_f32_16x16x32_bf16 v[92:95], v[148:151], v[204:207], v[92:95]
	v_mfma_f32_16x16x32_bf16 v[84:87], v[164:167], v[204:207], v[84:87]
	v_mfma_f32_16x16x32_bf16 v[76:79], v[148:151], v[212:215], v[76:79]
	v_mfma_f32_16x16x32_bf16 v[68:71], v[164:167], v[212:215], v[68:71]
	v_mfma_f32_16x16x32_bf16 v[124:127], v[168:171], v[184:187], v[124:127]
	v_mfma_f32_16x16x32_bf16 v[120:123], v[176:179], v[184:187], v[120:123]
	v_mfma_f32_16x16x32_bf16 v[116:119], v[168:171], v[192:195], v[116:119]
	v_mfma_f32_16x16x32_bf16 v[96:99], v[176:179], v[192:195], v[96:99]
	v_mfma_f32_16x16x32_bf16 v[88:91], v[168:171], v[200:203], v[88:91]
	v_mfma_f32_16x16x32_bf16 v[80:83], v[176:179], v[200:203], v[80:83]
	v_mfma_f32_16x16x32_bf16 v[72:75], v[168:171], v[208:211], v[72:75]
	v_mfma_f32_16x16x32_bf16 v[64:67], v[176:179], v[208:211], v[64:67]
	v_mfma_f32_16x16x32_bf16 v[124:127], v[172:175], v[188:191], v[124:127]
	v_mfma_f32_16x16x32_bf16 v[120:123], v[180:183], v[188:191], v[120:123]
	v_mfma_f32_16x16x32_bf16 v[116:119], v[172:175], v[196:199], v[116:119]
	v_mfma_f32_16x16x32_bf16 v[96:99], v[180:183], v[196:199], v[96:99]
	v_mfma_f32_16x16x32_bf16 v[88:91], v[172:175], v[204:207], v[88:91]
	v_mfma_f32_16x16x32_bf16 v[80:83], v[180:183], v[204:207], v[80:83]
	v_mfma_f32_16x16x32_bf16 v[72:75], v[172:175], v[212:215], v[72:75]
	v_mfma_f32_16x16x32_bf16 v[64:67], v[180:183], v[212:215], v[64:67]
	s_barrier
	s_add_i32 s46, s55, s9
	s_mov_b32 m0, s46
	ds_read_b128 v[184:187], v157 offset:16384
	ds_read_b128 v[188:191], v157 offset:17408
	ds_read_b128 v[192:195], v157 offset:18432
	ds_read_b128 v[196:199], v157 offset:19456
	ds_read_b128 v[200:203], v157 offset:20480
	ds_read_b128 v[204:207], v157 offset:21504
	ds_read_b128 v[208:211], v157 offset:22528
	ds_read_b128 v[212:215], v157 offset:23552
	global_load_lds_dwordx4 v132, s[48:49]
	s_add_i32 m0, s46, 0x2000
	s_add_u32 s46, s48, 0x104000
	s_addc_u32 s47, s49, 0
	s_add_i32 s64, s56, s9
	global_load_lds_dwordx4 v128, s[48:49]
	s_mov_b32 m0, s64
	s_nop 0
	global_load_lds_dwordx4 v132, s[46:47]
	s_add_i32 m0, s64, 0x2000
	s_nop 0
	global_load_lds_dwordx4 v128, s[46:47]
	s_waitcnt vmcnt(4)
	s_waitcnt lgkmcnt(0)
	s_barrier
	s_waitcnt lgkmcnt(0)
	v_mfma_f32_16x16x32_bf16 v[60:63], v[144:147], v[184:187], v[60:63]
	v_mfma_f32_16x16x32_bf16 v[52:55], v[160:163], v[184:187], v[52:55]
	v_mfma_f32_16x16x32_bf16 v[44:47], v[144:147], v[192:195], v[44:47]
	v_mfma_f32_16x16x32_bf16 v[36:39], v[160:163], v[192:195], v[36:39]
	v_mfma_f32_16x16x32_bf16 v[28:31], v[144:147], v[200:203], v[28:31]
	v_mfma_f32_16x16x32_bf16 v[20:23], v[160:163], v[200:203], v[20:23]
	v_mfma_f32_16x16x32_bf16 v[12:15], v[144:147], v[208:211], v[12:15]
	v_mfma_f32_16x16x32_bf16 v[4:7], v[160:163], v[208:211], v[4:7]
	v_mfma_f32_16x16x32_bf16 v[60:63], v[148:151], v[188:191], v[60:63]
	v_mfma_f32_16x16x32_bf16 v[52:55], v[164:167], v[188:191], v[52:55]
	v_mfma_f32_16x16x32_bf16 v[44:47], v[148:151], v[196:199], v[44:47]
	v_mfma_f32_16x16x32_bf16 v[36:39], v[164:167], v[196:199], v[36:39]
	v_mfma_f32_16x16x32_bf16 v[28:31], v[148:151], v[204:207], v[28:31]
	v_mfma_f32_16x16x32_bf16 v[20:23], v[164:167], v[204:207], v[20:23]
	v_mfma_f32_16x16x32_bf16 v[12:15], v[148:151], v[212:215], v[12:15]
	v_mfma_f32_16x16x32_bf16 v[4:7], v[164:167], v[212:215], v[4:7]
	v_mfma_f32_16x16x32_bf16 v[56:59], v[168:171], v[184:187], v[56:59]
	v_mfma_f32_16x16x32_bf16 v[48:51], v[176:179], v[184:187], v[48:51]
	v_mfma_f32_16x16x32_bf16 v[40:43], v[168:171], v[192:195], v[40:43]
	v_mfma_f32_16x16x32_bf16 v[32:35], v[176:179], v[192:195], v[32:35]
	v_mfma_f32_16x16x32_bf16 v[24:27], v[168:171], v[200:203], v[24:27]
	v_mfma_f32_16x16x32_bf16 v[16:19], v[176:179], v[200:203], v[16:19]
	v_mfma_f32_16x16x32_bf16 v[8:11], v[168:171], v[208:211], v[8:11]
	v_mfma_f32_16x16x32_bf16 v[0:3], v[176:179], v[208:211], v[0:3]
	v_mfma_f32_16x16x32_bf16 v[56:59], v[172:175], v[188:191], v[56:59]
	v_mfma_f32_16x16x32_bf16 v[48:51], v[180:183], v[188:191], v[48:51]
	v_mfma_f32_16x16x32_bf16 v[40:43], v[172:175], v[196:199], v[40:43]
	v_mfma_f32_16x16x32_bf16 v[32:35], v[180:183], v[196:199], v[32:35]
	v_mfma_f32_16x16x32_bf16 v[24:27], v[172:175], v[204:207], v[24:27]
	v_mfma_f32_16x16x32_bf16 v[16:19], v[180:183], v[204:207], v[16:19]
	v_mfma_f32_16x16x32_bf16 v[8:11], v[172:175], v[212:215], v[8:11]
	v_mfma_f32_16x16x32_bf16 v[0:3], v[180:183], v[212:215], v[0:3]
	s_barrier
; #define PG8_STAGE(bufoff, gbase, voff) do { _Pragma("unroll") for (int _i = 0; _i < 2; ++_i) \
;         __builtin_amdgcn_global_load_lds((const unsigned*)((const char*)(gbase) + (voff)[_i]), (PG8_LAS unsigned*)(lds + (bufoff) + ldsw + _i * 8192), 16, 0, 0); } while (0)
; template <class Epi, class Sched, bool ALIGN_EPI = false, bool SP2 = false>
; __device__ __forceinline__ void gemm_phase(PG8_LAS unsigned char* lds, const Gemm g, const Sched& S, const Epi& E, int wid) {
;     ...
;             PG8_LDB(B0, 1, 0); PG8_LDB(B1, 1, 1); PG8_SCHED; PG8_LDA(At, 1, 0); PG8_STAGE(PG8_SA(0, 1), a2 + hstepA, voffA);
;             PG8_WAIT_V(8); PG8_WAIT_L(0); PG8_BAR; PG8_MMA(0, 0, At, B0); PG8_MMA(0, 1, At, B1); PG8_BAR; PG8_SCHED;
;             PG8_LDA(At, 1, 1); PG8_STAGE_NT(PG8_SB(1, 0), b3, voffB); PG8_STAGE_NT(PG8_SB(1, 1), b3 + hstepB, voffB); PG8_STAGE(PG8_SA(1, 0), a3, voffA);
;             PG8_WAIT_V(8); PG8_WAIT_L(0); PG8_BAR; PG8_MMA(1, 0, At, B0); PG8_MMA(1, 1, At, B1); PG8_BAR; PG8_SCHED;
;             } else {
;             PG8_LDB(B0, 0, 0); PG8_SCHED; PG8_LDA(At, 0, 0); PG8_STAGE(PG8_SA(1, 1), a1 + hstepA, voffA);
;             PG8_WAIT_L(8); PG8_BAR; PG8_WAIT_L(0); PG8_MMA(0, 0, At, B0); PG8_BAR; PG8_SCHED;
;             PG8_LDB(B1, 0, 1); PG8_STAGE_NT(PG8_SB(0, 0), b2, voffB);
;             PG8_BAR; PG8_WAIT_L(0); PG8_MMA(0, 1, At, B1); PG8_BAR;
;             PG8_LDA(At, 0, 1); PG8_STAGE(PG8_SA(0, 0), a2, voffA);
;             PG8_BAR; PG8_WAIT_L(0); PG8_MMA(1, 0, At, B0); PG8_BAR; PG8_SCHED;
;             PG8_STAGE_NT(PG8_SB(0, 1), b2 + hstepB, voffB);
;             PG8_WAIT_V(6); PG8_BAR; PG8_MMA(1, 1, At, B1); PG8_BAR;
;             PG8_LDB(B0, 1, 0); PG8_SCHED; PG8_LDA(At, 1, 0); PG8_STAGE(PG8_SA(0, 1), a2 + hstepA, voffA);
;             PG8_WAIT_L(8); PG8_BAR; PG8_WAIT_L(0); PG8_MMA(0, 0, At, B0); PG8_BAR; PG8_SCHED;
;             PG8_LDB(B1, 1, 1); PG8_STAGE_NT(PG8_SB(1, 0), b3, voffB);
;             PG8_BAR; PG8_WAIT_L(0); PG8_MMA(0, 1, At, B1); PG8_BAR;
;             PG8_LDA(At, 1, 1); PG8_STAGE(PG8_SA(1, 0), a3, voffA);
;             PG8_BAR; PG8_WAIT_L(0); PG8_MMA(1, 0, At, B0); PG8_BAR; PG8_SCHED;
;             PG8_STAGE_NT(PG8_SB(1, 1), b3 + hstepB, voffB);
;             PG8_WAIT_V(6); PG8_BAR; PG8_MMA(1, 1, At, B1); PG8_BAR;
;             }
;         }
;         if constexpr (ALIGN_EPI) { if (wr == 0) PG8_BAR; }
	s_add_i32 s64, 0, 0x18000
	v_add_u32_e32 v159, s64, v153
	s_add_i32 s65, 0, 0x1c000
	ds_read_b128 v[144:147], v159
	ds_read_b128 v[148:151], v159 offset:1024
	ds_read_b128 v[160:163], v159 offset:2048
	ds_read_b128 v[164:167], v159 offset:3072
	v_add_u32_e32 v159, s65, v153
	ds_read_b128 v[168:171], v159
	ds_read_b128 v[172:175], v159 offset:1024
	ds_read_b128 v[176:179], v159 offset:2048
	ds_read_b128 v[180:183], v159 offset:3072
	s_add_u32 s46, s50, 0x104000
	s_addc_u32 s47, s51, 0
	s_mov_b32 m0, s24
	ds_read_b128 v[184:187], v157 offset:32768
	ds_read_b128 v[188:191], v157 offset:33792
	ds_read_b128 v[192:195], v157 offset:34816
	ds_read_b128 v[196:199], v157 offset:35840
	ds_read_b128 v[200:203], v157 offset:36864
	ds_read_b128 v[204:207], v157 offset:37888
	ds_read_b128 v[208:211], v157 offset:38912
	ds_read_b128 v[212:215], v157 offset:39936
	global_load_lds_dwordx4 v134, s[46:47]
	s_mov_b32 m0, s25
	s_nop 0
	global_load_lds_dwordx4 v130, s[46:47]
	s_mov_b32 m0, s22
	s_nop 0
	global_load_lds_dwordx4 v134, s[50:51]
	s_mov_b32 m0, s23
	s_nop 0
	global_load_lds_dwordx4 v130, s[50:51]
	s_waitcnt vmcnt(8)
	s_waitcnt lgkmcnt(0)
	s_barrier
	s_waitcnt lgkmcnt(0)
	v_mfma_f32_16x16x32_bf16 v[112:115], v[144:147], v[184:187], v[112:115]
	v_mfma_f32_16x16x32_bf16 v[108:111], v[160:163], v[184:187], v[108:111]
	v_mfma_f32_16x16x32_bf16 v[104:107], v[144:147], v[192:195], v[104:107]
	v_mfma_f32_16x16x32_bf16 v[100:103], v[160:163], v[192:195], v[100:103]
	v_mfma_f32_16x16x32_bf16 v[92:95], v[144:147], v[200:203], v[92:95]
	v_mfma_f32_16x16x32_bf16 v[84:87], v[160:163], v[200:203], v[84:87]
	v_mfma_f32_16x16x32_bf16 v[76:79], v[144:147], v[208:211], v[76:79]
	v_mfma_f32_16x16x32_bf16 v[68:71], v[160:163], v[208:211], v[68:71]
	v_mfma_f32_16x16x32_bf16 v[112:115], v[148:151], v[188:191], v[112:115]
	v_mfma_f32_16x16x32_bf16 v[108:111], v[164:167], v[188:191], v[108:111]
	v_mfma_f32_16x16x32_bf16 v[104:107], v[148:151], v[196:199], v[104:107]
	v_mfma_f32_16x16x32_bf16 v[100:103], v[164:167], v[196:199], v[100:103]
	v_mfma_f32_16x16x32_bf16 v[92:95], v[148:151], v[204:207], v[92:95]
	v_mfma_f32_16x16x32_bf16 v[84:87], v[164:167], v[204:207], v[84:87]
	v_mfma_f32_16x16x32_bf16 v[76:79], v[148:151], v[212:215], v[76:79]
	v_mfma_f32_16x16x32_bf16 v[68:71], v[164:167], v[212:215], v[68:71]
	v_mfma_f32_16x16x32_bf16 v[124:127], v[168:171], v[184:187], v[124:127]
	v_mfma_f32_16x16x32_bf16 v[120:123], v[176:179], v[184:187], v[120:123]
	v_mfma_f32_16x16x32_bf16 v[116:119], v[168:171], v[192:195], v[116:119]
	v_mfma_f32_16x16x32_bf16 v[96:99], v[176:179], v[192:195], v[96:99]
	v_mfma_f32_16x16x32_bf16 v[88:91], v[168:171], v[200:203], v[88:91]
	v_mfma_f32_16x16x32_bf16 v[80:83], v[176:179], v[200:203], v[80:83]
	v_mfma_f32_16x16x32_bf16 v[72:75], v[168:171], v[208:211], v[72:75]
	v_mfma_f32_16x16x32_bf16 v[64:67], v[176:179], v[208:211], v[64:67]
	v_mfma_f32_16x16x32_bf16 v[124:127], v[172:175], v[188:191], v[124:127]
	v_mfma_f32_16x16x32_bf16 v[120:123], v[180:183], v[188:191], v[120:123]
	v_mfma_f32_16x16x32_bf16 v[116:119], v[172:175], v[196:199], v[116:119]
	v_mfma_f32_16x16x32_bf16 v[96:99], v[180:183], v[196:199], v[96:99]
	v_mfma_f32_16x16x32_bf16 v[88:91], v[172:175], v[204:207], v[88:91]
	v_mfma_f32_16x16x32_bf16 v[80:83], v[180:183], v[204:207], v[80:83]
	v_mfma_f32_16x16x32_bf16 v[72:75], v[172:175], v[212:215], v[72:75]
	v_mfma_f32_16x16x32_bf16 v[64:67], v[180:183], v[212:215], v[64:67]
	s_barrier
	s_add_i32 s46, s64, s9
	s_mov_b32 m0, s46
	s_add_u32 s98, s48, 0x80
	s_addc_u32 s99, s49, 0
	ds_read_b128 v[184:187], v157 offset:49152
	ds_read_b128 v[188:191], v157 offset:50176
	ds_read_b128 v[192:195], v157 offset:51200
	ds_read_b128 v[196:199], v157 offset:52224
	ds_read_b128 v[200:203], v157 offset:53248
	ds_read_b128 v[204:207], v157 offset:54272
	ds_read_b128 v[208:211], v157 offset:55296
	ds_read_b128 v[212:215], v157 offset:56320
	global_load_lds_dwordx4 v132, s[98:99]
	s_add_i32 m0, s46, 0x2000
	s_add_u32 s46, s48, 0x104080
	s_addc_u32 s47, s49, 0
	s_add_i32 s48, s65, s9
	global_load_lds_dwordx4 v128, s[98:99]
	s_mov_b32 m0, s48
	s_nop 0
	global_load_lds_dwordx4 v132, s[46:47]
	s_add_i32 m0, s48, 0x2000
	s_nop 0
	global_load_lds_dwordx4 v128, s[46:47]
	s_waitcnt vmcnt(4)
	s_waitcnt lgkmcnt(0)
	s_barrier
	s_waitcnt lgkmcnt(0)
	v_mfma_f32_16x16x32_bf16 v[60:63], v[144:147], v[184:187], v[60:63]
	v_mfma_f32_16x16x32_bf16 v[52:55], v[160:163], v[184:187], v[52:55]
	v_mfma_f32_16x16x32_bf16 v[44:47], v[144:147], v[192:195], v[44:47]
	v_mfma_f32_16x16x32_bf16 v[36:39], v[160:163], v[192:195], v[36:39]
	v_mfma_f32_16x16x32_bf16 v[28:31], v[144:147], v[200:203], v[28:31]
	v_mfma_f32_16x16x32_bf16 v[20:23], v[160:163], v[200:203], v[20:23]
	v_mfma_f32_16x16x32_bf16 v[12:15], v[144:147], v[208:211], v[12:15]
	v_mfma_f32_16x16x32_bf16 v[4:7], v[160:163], v[208:211], v[4:7]
	v_mfma_f32_16x16x32_bf16 v[60:63], v[148:151], v[188:191], v[60:63]
	v_mfma_f32_16x16x32_bf16 v[52:55], v[164:167], v[188:191], v[52:55]
	v_mfma_f32_16x16x32_bf16 v[44:47], v[148:151], v[196:199], v[44:47]
	v_mfma_f32_16x16x32_bf16 v[36:39], v[164:167], v[196:199], v[36:39]
	v_mfma_f32_16x16x32_bf16 v[28:31], v[148:151], v[204:207], v[28:31]
	v_mfma_f32_16x16x32_bf16 v[20:23], v[164:167], v[204:207], v[20:23]
	v_mfma_f32_16x16x32_bf16 v[12:15], v[148:151], v[212:215], v[12:15]
	v_mfma_f32_16x16x32_bf16 v[4:7], v[164:167], v[212:215], v[4:7]
	v_mfma_f32_16x16x32_bf16 v[56:59], v[168:171], v[184:187], v[56:59]
	v_mfma_f32_16x16x32_bf16 v[48:51], v[176:179], v[184:187], v[48:51]
	v_mfma_f32_16x16x32_bf16 v[40:43], v[168:171], v[192:195], v[40:43]
	v_mfma_f32_16x16x32_bf16 v[32:35], v[176:179], v[192:195], v[32:35]
	v_mfma_f32_16x16x32_bf16 v[24:27], v[168:171], v[200:203], v[24:27]
	v_mfma_f32_16x16x32_bf16 v[16:19], v[176:179], v[200:203], v[16:19]
	v_mfma_f32_16x16x32_bf16 v[8:11], v[168:171], v[208:211], v[8:11]
	v_mfma_f32_16x16x32_bf16 v[0:3], v[176:179], v[208:211], v[0:3]
	v_mfma_f32_16x16x32_bf16 v[56:59], v[172:175], v[188:191], v[56:59]
	v_mfma_f32_16x16x32_bf16 v[48:51], v[180:183], v[188:191], v[48:51]
	v_mfma_f32_16x16x32_bf16 v[40:43], v[172:175], v[196:199], v[40:43]
	v_mfma_f32_16x16x32_bf16 v[32:35], v[180:183], v[196:199], v[32:35]
	v_mfma_f32_16x16x32_bf16 v[24:27], v[172:175], v[204:207], v[24:27]
	v_mfma_f32_16x16x32_bf16 v[16:19], v[180:183], v[204:207], v[16:19]
	v_mfma_f32_16x16x32_bf16 v[8:11], v[172:175], v[212:215], v[8:11]
	v_mfma_f32_16x16x32_bf16 v[0:3], v[180:183], v[212:215], v[0:3]
	s_barrier
	s_add_i32 s63, s63, 2
	s_add_u32 s61, s61, 0x100
	s_addc_u32 s62, s62, 0
	s_cmp_gt_u32 s63, 61
	s_mov_b64 s[46:47], s[4:5]
	s_cbranch_scc0 .LBB0_1133
	s_and_b64 vcc, exec, s[40:41]
	s_cbranch_vccz .LBB0_1136
	s_barrier

; __device__ __forceinline__ int fresh_lane() { int l; asm volatile("v_mbcnt_lo_u32_b32 %0, -1, 0\n\tv_mbcnt_hi_u32_b32 %0, -1, %0" : "=v"(l)); return l; }
; #define LAS __attribute__((address_space(3)))
; __global__ void __launch_bounds__(NWAVES * 64, 2) fwd(Args args) {
;     extern __shared__ __attribute__((aligned(16))) unsigned char lds[];
;     LAS unsigned char* L = (LAS unsigned char*)lds;
;     volatile LAS unsigned* MISC = (volatile LAS unsigned*)(L + MISC_OFF);
;     const int wave = __builtin_amdgcn_readfirstlane((int)threadIdx.x >> 6);
;     int lane = fresh_lane(), tid = wave * 64 + lane;
	.amdhsa_kernel _Z3fwd4Args
		.amdhsa_group_segment_fixed_size 0
		.amdhsa_private_segment_fixed_size 0
		.amdhsa_kernarg_size 416
		.amdhsa_user_sgpr_count 2
		.amdhsa_user_sgpr_dispatch_ptr 0
		.amdhsa_user_sgpr_queue_ptr 0
		.amdhsa_user_sgpr_kernarg_segment_ptr 1
		.amdhsa_user_sgpr_dispatch_id 0
		.amdhsa_user_sgpr_kernarg_preload_length 0
		.amdhsa_user_sgpr_kernarg_preload_offset 0
		.amdhsa_user_sgpr_private_segment_size 0
		.amdhsa_uses_dynamic_stack 0
		.amdhsa_enable_private_segment 0
		.amdhsa_system_sgpr_workgroup_id_x 1
		.amdhsa_system_sgpr_workgroup_id_y 0
		.amdhsa_system_sgpr_workgroup_id_z 0
		.amdhsa_system_sgpr_workgroup_info 0
		.amdhsa_system_vgpr_workitem_id 0
		.amdhsa_next_free_vgpr 241
		.amdhsa_next_free_sgpr 102
		.amdhsa_accum_offset 244
		.amdhsa_reserve_vcc 1
		.amdhsa_float_round_mode_32 0
		.amdhsa_float_round_mode_16_64 0
		.amdhsa_float_denorm_mode_32 3
		.amdhsa_float_denorm_mode_16_64 3
		.amdhsa_dx10_clamp 1
		.amdhsa_ieee_mode 1
		.amdhsa_fp16_overflow 0
		.amdhsa_tg_split 0
		.amdhsa_exception_fp_ieee_invalid_op 0
		.amdhsa_exception_fp_denorm_src 0
		.amdhsa_exception_fp_ieee_div_zero 0
		.amdhsa_exception_fp_ieee_overflow 0
		.amdhsa_exception_fp_ieee_underflow 0
		.amdhsa_exception_fp_ieee_inexact 0
		.amdhsa_exception_int_div_zero 0
	.end_amdhsa_kernel

; __device__ __forceinline__ int fresh_lane() { int l; asm volatile("v_mbcnt_lo_u32_b32 %0, -1, 0\n\tv_mbcnt_hi_u32_b32 %0, -1, %0" : "=v"(l)); return l; }
; #define LAS __attribute__((address_space(3)))
; __global__ void __launch_bounds__(NWAVES * 64, 2) fwd(Args args) {
;     extern __shared__ __attribute__((aligned(16))) unsigned char lds[];
;     LAS unsigned char* L = (LAS unsigned char*)lds;
;     volatile LAS unsigned* MISC = (volatile LAS unsigned*)(L + MISC_OFF);
;     const int wave = __builtin_amdgcn_readfirstlane((int)threadIdx.x >> 6);
;     int lane = fresh_lane(), tid = wave * 64 + lane;
amdhsa.kernels:
  - .agpr_count:     0
    .args:
      - .offset:         0
        .size:           160
        .value_kind:     by_value
      - .offset:         160
        .size:           4
        .value_kind:     hidden_block_count_x
      - .offset:         164
        .size:           4
        .value_kind:     hidden_block_count_y
      - .offset:         168
        .size:           4
        .value_kind:     hidden_block_count_z
      - .offset:         172
        .size:           2
        .value_kind:     hidden_group_size_x
      - .offset:         174
        .size:           2
        .value_kind:     hidden_group_size_y
      - .offset:         176
        .size:           2
        .value_kind:     hidden_group_size_z
      - .offset:         178
        .size:           2
        .value_kind:     hidden_remainder_x
      - .offset:         180
        .size:           2
        .value_kind:     hidden_remainder_y
      - .offset:         182
        .size:           2
        .value_kind:     hidden_remainder_z
      - .offset:         200
        .size:           8
        .value_kind:     hidden_global_offset_x
      - .offset:         208
        .size:           8
        .value_kind:     hidden_global_offset_y
      - .offset:         216
        .size:           8
        .value_kind:     hidden_global_offset_z
      - .offset:         224
        .size:           2
        .value_kind:     hidden_grid_dims
      - .offset:         280
        .size:           4
        .value_kind:     hidden_dynamic_lds_size
    .group_segment_fixed_size: 0
    .kernarg_segment_align: 8
    .kernarg_segment_size: 416
    .language:       OpenCL C
    .language_version:
      - 2
      - 0
    .max_flat_workgroup_size: 512
    .name:           _Z3fwd4Args
    .private_segment_fixed_size: 0
    .sgpr_count:     108
    .sgpr_spill_count: 10
    .symbol:         _Z3fwd4Args.kd
    .uniform_work_group_size: 1
    .uses_dynamic_stack: false
    .vgpr_count:     241
    .vgpr_spill_count: 0
    .wavefront_size: 64
